# plus ticketed norm: wave_sum butterflies via permlane32/16 swaps and DPP adds instead of six ds_bpermute round trips (same pairing order)
# baseline (speedup 1.0000x reference)
;     __device__ __forceinline__ float* CX() const { return (float*)(ws + OFF_CX); }
;     __device__ __forceinline__ float* Y() const { return (float*)(ws + OFF_Y); }
; __device__ __forceinline__ float wave_sum(float v) {
;     v += __shfl_xor(v, 32); v += __shfl_xor(v, 16); v += __shfl_xor(v, 8); v += __shfl_xor(v, 4); v += __shfl_xor(v, 2); v += __shfl_xor(v, 1); return v;
; }
; template <bool HOIST>
; __device__ __forceinline__ void norm_rows(const Params& p, int chunk, int layer, int row_begin, int row_end, int row_step) {
;     ...
;     for (int row = row_begin + wave; row < row_end; row += row_step) {
;         const int bl = row / TT, t = row - bl * TT, b = chunk * CB + bl;
;         const bool isctx = t < CTXL;
;         if (layer == NLAY - 1 && isctx) continue;
;         const float* xin; float* xst; int mr;
;         if (isctx) { const size_t o = ((size_t)b * CTXL + t) * DM; xin = (layer <= 0 ? p.ctx : (const float*)p.CX()) + o; xst = p.CX() + o; mr = 16; }
;         else { const size_t o = ((size_t)b * SEQ + (t - CTXL)) * DM; xin = (layer <= 0 ? p.x : (const float*)p.out) + o; xst = p.out + o; mr = b; }
;         if (!HOIST) load_vecs(mr);
;         float4 xv[4];
; #pragma unroll
;         for (int i = 0; i < 4; i++) { const f32x4 t4 = __builtin_nontemporal_load((const f32x4*)(xin + i * 256 + lane * 4)); xv[i] = make_float4(t4[0], t4[1], t4[2], t4[3]); }
;         if (layer >= 0) {
;             const bf16_t* yr = (const bf16_t*)p.Y() + (size_t)row * DM;
;             float4 yv[4]; float ss = 0.f;
; #pragma unroll
;             for (int i = 0; i < 4; i++) { const u32x2 w = __builtin_nontemporal_load((const u32x2*)(yr + i * 256 + lane * 4)); yv[i] = make_float4(bflo(w[0]), bfhi(w[0]), bflo(w[1]), bfhi(w[1]));
;                 ss += yv[i].x * yv[i].x + yv[i].y * yv[i].y + yv[i].z * yv[i].z + yv[i].w * yv[i].w; }
;             ss = wave_sum(ss);
;             const float rstd = rsqrtf(ss * (1.f / DM) + 1e-6f);
; #pragma unroll
;             for (int i = 0; i < 4; i++) {
;                 const int e = i * 256 + lane * 4;
;                 xv[i].x += gq[i].x * (yv[i].x * rstd); xv[i].y += gq[i].y * (yv[i].y * rstd);
;                 xv[i].z += gq[i].z * (yv[i].z * rstd); xv[i].w += gq[i].w * (yv[i].w * rstd);
;                 __builtin_nontemporal_store((f32x4){xv[i].x, xv[i].y, xv[i].z, xv[i].w}, (f32x4*)(xst + e));
;             }
.LBB0_655:
	v_mul_hi_i32 v18, v66, s33
	v_lshrrev_b32_e32 v19, 31, v18
	v_ashrrev_i32_e32 v18, 9, v18
	v_add_u32_e32 v26, v18, v19
	s_movk_i32 s16, 0xf700
	v_mad_i32_i24 v20, v26, s16, v66
	v_cmp_lt_i32_e32 vcc, s29, v20
	s_xor_b64 s[16:17], s[78:79], -1
	s_or_b64 s[16:17], s[16:17], vcc
	s_and_saveexec_b64 s[54:55], s[16:17]
	s_cbranch_execz .LBB0_654
	s_and_saveexec_b64 s[16:17], vcc
	s_xor_b64 s[56:57], exec, s[16:17]
	v_add_u32_e32 v18, 0xffffff00, v20
	v_mov_b32_e32 v19, v1
	s_or_saveexec_b64 s[56:57], s[56:57]
	v_readlane_b32 s60, v253, 19
	v_readlane_b32 s74, v253, 33
	v_readlane_b32 s75, v253, 34
	v_mov_b64_e32 v[22:23], 21
	v_mov_b64_e32 v[20:21], s[10:11]
	v_mov_b64_e32 v[24:25], s[74:75]
	v_readlane_b32 s61, v253, 20
	v_readlane_b32 s62, v253, 21
	v_readlane_b32 s63, v253, 22
	v_readlane_b32 s64, v253, 23
	v_readlane_b32 s65, v253, 24
	v_readlane_b32 s66, v253, 25
	v_readlane_b32 s67, v253, 26
	v_readlane_b32 s68, v253, 27
	v_readlane_b32 s69, v253, 28
	v_readlane_b32 s70, v253, 29
	v_readlane_b32 s71, v253, 30
	v_readlane_b32 s72, v253, 31
	v_readlane_b32 s73, v253, 32
	s_xor_b64 exec, exec, s[56:57]
	v_mul_i32_i24_e32 v18, 0xfffff700, v26
	v_ashrrev_i32_e32 v19, 31, v18
	v_lshl_add_u64 v[18:19], v[66:67], 0, v[18:19]
	v_mov_b64_e32 v[22:23], 18
	v_mov_b64_e32 v[20:21], s[12:13]
	v_mov_b64_e32 v[24:25], s[76:77]
	s_or_b64 exec, exec, s[56:57]
	v_add_u32_e32 v26, s95, v26
	v_ashrrev_i32_e32 v27, 31, v26
	v_lshlrev_b64 v[22:23], v22, v[26:27]
	v_lshlrev_b64 v[18:19], 10, v[18:19]
	v_lshl_add_u64 v[18:19], v[18:19], 0, v[22:23]
	v_lshlrev_b64 v[18:19], 2, v[18:19]
	v_lshl_add_u64 v[20:21], v[20:21], 0, v[18:19]
	v_lshl_add_u64 v[70:71], v[24:25], 0, v[18:19]
	v_lshl_add_u64 v[18:19], v[20:21], 0, v[0:1]
	global_load_dwordx4 v[30:33], v[18:19], off nt
	global_load_dwordx4 v[26:29], v[18:19], off offset:1024 nt
	global_load_dwordx4 v[22:25], v[18:19], off offset:2048 nt
	s_nop 0
	global_load_dwordx4 v[18:21], v[18:19], off offset:3072 nt
	s_nop 0
	global_load_dwordx2 v[80:81], v[68:69], off nt
	global_load_dwordx2 v[82:83], v[68:69], off offset:512 nt
	global_load_dwordx2 v[84:85], v[68:69], off offset:1024 nt
	global_load_dwordx2 v[86:87], v[68:69], off offset:1536 nt
	v_cmp_lt_i32_e32 vcc, v179, v180
	s_mov_b32 s16, 0x800000
	v_lshl_add_u64 v[70:71], v[70:71], 0, v[0:1]
	v_cndmask_b32_e32 v72, v178, v179, vcc
	v_cmp_lt_i32_e32 vcc, v181, v180
	v_lshlrev_b32_e32 v74, 2, v72
	s_waitcnt vmcnt(3)
	v_and_b32_e32 v89, 0xffff0000, v80
	v_cndmask_b32_e32 v72, v178, v181, vcc
	v_cmp_lt_i32_e32 vcc, v182, v180
	v_lshlrev_b32_e32 v75, 2, v72
	s_waitcnt vmcnt(2)
	v_and_b32_e32 v91, 0xffff0000, v82
	v_cndmask_b32_e32 v72, v178, v182, vcc
	v_cmp_lt_i32_e32 vcc, v183, v180
	v_lshlrev_b32_e32 v76, 2, v72
	v_lshlrev_b32_e32 v88, 16, v80
	v_cndmask_b32_e32 v72, v178, v183, vcc
	v_cmp_lt_i32_e32 vcc, v184, v180
	v_lshlrev_b32_e32 v77, 2, v72
	v_lshlrev_b32_e32 v90, 16, v82
	v_cndmask_b32_e32 v72, v178, v184, vcc
	v_cmp_lt_i32_e32 vcc, v185, v180
	v_lshlrev_b32_e32 v78, 2, v72
	v_mov_b32_e32 v96, v89
	v_cndmask_b32_e32 v72, v178, v185, vcc
	v_mov_b32_e32 v97, v91
	v_lshlrev_b32_e32 v79, 2, v72
	v_lshlrev_b32_e32 v72, 16, v81
	v_lshlrev_b32_e32 v80, 16, v83
	v_mov_b32_e32 v94, v88
	v_mov_b32_e32 v95, v90
	v_pk_mul_f32 v[96:97], v[96:97], v[96:97]
	v_and_b32_e32 v73, 0xffff0000, v81
	v_and_b32_e32 v81, 0xffff0000, v83
	v_mov_b32_e32 v82, v72
	v_mov_b32_e32 v83, v80
	v_pk_fma_f32 v[94:95], v[94:95], v[94:95], v[96:97]
	s_waitcnt vmcnt(0)
	v_and_b32_e32 v97, 0xffff0000, v86
	v_pk_fma_f32 v[82:83], v[82:83], v[82:83], v[94:95]
	v_and_b32_e32 v95, 0xffff0000, v84
	v_mov_b32_e32 v92, v73
	v_mov_b32_e32 v93, v81
	v_lshlrev_b32_e32 v94, 16, v84
	v_lshlrev_b32_e32 v96, 16, v86
	v_mov_b32_e32 v102, v95
	v_mov_b32_e32 v103, v97
	v_pk_fma_f32 v[82:83], v[92:93], v[92:93], v[82:83]
	v_lshlrev_b32_e32 v92, 16, v85
	v_lshlrev_b32_e32 v84, 16, v87
	v_mov_b32_e32 v100, v94
	v_mov_b32_e32 v101, v96
	v_pk_mul_f32 v[102:103], v[102:103], v[102:103]
	v_and_b32_e32 v93, 0xffff0000, v85
	v_and_b32_e32 v85, 0xffff0000, v87
	v_mov_b32_e32 v86, v92
	v_mov_b32_e32 v87, v84
	v_pk_fma_f32 v[100:101], v[100:101], v[100:101], v[102:103]
	v_mov_b32_e32 v98, v93
	v_mov_b32_e32 v99, v85
	v_pk_fma_f32 v[86:87], v[86:87], v[86:87], v[100:101]
	v_add_f32_e32 v82, v82, v83
	v_pk_fma_f32 v[86:87], v[98:99], v[98:99], v[86:87]
	s_nop 0
	v_add_f32_e32 v82, v82, v86
	v_add_f32_e32 v82, v82, v87
	v_mov_b32_e32 v83, v82
	s_nop 1
	v_permlane32_swap_b32_e32 v82, v83
	v_add_f32_e32 v82, v82, v83
	v_mov_b32_e32 v83, v82
	s_nop 1
	v_permlane16_swap_b32_e32 v82, v83
	v_add_f32_e32 v82, v82, v83
	s_nop 1
	v_add_f32_dpp v82, v82, v82 row_ror:8 row_mask:0xf bank_mask:0xf
	s_nop 1
	v_add_f32_dpp v82, v82, v82 row_ror:4 row_mask:0xf bank_mask:0xf
	s_nop 1
	v_add_f32_dpp v82, v82, v82 quad_perm:[2,3,0,1] row_mask:0xf bank_mask:0xf
	s_nop 1
	v_add_f32_dpp v82, v82, v82 quad_perm:[1,0,3,2] row_mask:0xf bank_mask:0xf
	s_nop 0
	v_fmamk_f32 v82, v82, 0x3a800000, v170
	v_cmp_gt_f32_e32 vcc, s16, v82
	v_mul_f32_e32 v83, 0x4b800000, v82
	s_nop 0
	v_cndmask_b32_e32 v82, v82, v83, vcc
	v_rsq_f32_e32 v82, v82
	s_nop 0
	v_mul_f32_e32 v83, 0x45800000, v82
	v_cndmask_b32_e32 v82, v82, v83, vcc
	v_pk_mul_f32 v[72:73], v[82:83], v[72:73] op_sel_hi:[0,1]
	v_pk_fma_f32 v[32:33], v[40:41], v[72:73], v[32:33]
	v_pk_mul_f32 v[72:73], v[82:83], v[90:91] op_sel_hi:[0,1]
	v_pk_fma_f32 v[26:27], v[46:47], v[72:73], v[26:27]
	v_pk_mul_f32 v[72:73], v[82:83], v[80:81] op_sel_hi:[0,1]
	v_pk_fma_f32 v[28:29], v[48:49], v[72:73], v[28:29]
	v_pk_mul_f32 v[72:73], v[82:83], v[94:95] op_sel_hi:[0,1]
	v_pk_fma_f32 v[22:23], v[34:35], v[72:73], v[22:23]
	v_pk_mul_f32 v[72:73], v[82:83], v[92:93] op_sel_hi:[0,1]
	v_pk_fma_f32 v[24:25], v[36:37], v[72:73], v[24:25]
	v_pk_mul_f32 v[72:73], v[82:83], v[96:97] op_sel_hi:[0,1]
	v_pk_mul_f32 v[86:87], v[82:83], v[88:89] op_sel_hi:[0,1]
	v_pk_fma_f32 v[18:19], v[42:43], v[72:73], v[18:19]
	v_pk_mul_f32 v[72:73], v[82:83], v[84:85] op_sel_hi:[0,1]
	v_pk_fma_f32 v[30:31], v[38:39], v[86:87], v[30:31]
	v_pk_fma_f32 v[20:21], v[44:45], v[72:73], v[20:21]
	s_and_b64 vcc, exec, s[0:1]
	global_store_dwordx4 v[70:71], v[30:33], off nt
	global_store_dwordx4 v[70:71], v[26:29], off offset:1024 nt
	global_store_dwordx4 v[70:71], v[22:25], off offset:2048 nt
	global_store_dwordx4 v[70:71], v[18:21], off offset:3072 nt
	s_cbranch_vccnz .LBB0_654
;     __device__ __forceinline__ bf16_t* H() const { return (bf16_t*)(ws + OFF_H); }
; __device__ __forceinline__ unsigned pk2(float lo, float hi) { const f32x2_t f = {lo, hi}; const bf16x2_t b = __builtin_convertvector(f, bf16x2_t); return __builtin_bit_cast(unsigned, b); }
; __device__ __forceinline__ float wave_sum(float v) {
;     v += __shfl_xor(v, 32); v += __shfl_xor(v, 16); v += __shfl_xor(v, 8); v += __shfl_xor(v, 4); v += __shfl_xor(v, 2); v += __shfl_xor(v, 1); return v;
; }
; template <bool HOIST>
; __device__ __forceinline__ void norm_rows(const Params& p, int chunk, int layer, int row_begin, int row_end, int row_step) {
;     ...
;         if (layer < NLAY - 1) {
;             float ss = 0.f;
; #pragma unroll
;             for (int i = 0; i < 4; i++) ss += xv[i].x * xv[i].x + xv[i].y * xv[i].y + xv[i].z * xv[i].z + xv[i].w * xv[i].w;
;             ss = wave_sum(ss);
;             const float rstd = rsqrtf(ss * (1.f / DM) + 1e-6f);
; #pragma unroll
;             for (int i = 0; i < 4; i++) {
;                 const int e = i * 256 + lane * 4;
;                 const float h0 = xv[i].x * rstd * ga[i].x + sh[i].x, h1 = xv[i].y * rstd * ga[i].y + sh[i].y;
;                 const float h2 = xv[i].z * rstd * ga[i].z + sh[i].z, h3 = xv[i].w * rstd * ga[i].w + sh[i].w;
;                 *(uint2*)(p.H() + (size_t)row * DM + e) = make_uint2(pk2(h0, h1), pk2(h2, h3));
;             }
;         }
	v_mov_b32_e32 v70, v26
	v_mov_b32_e32 v71, v30
	v_pk_mul_f32 v[70:71], v[70:71], v[70:71]
	v_mov_b32_e32 v72, v27
	v_mov_b32_e32 v73, v31
	v_pk_fma_f32 v[70:71], v[72:73], v[72:73], v[70:71]
	v_mov_b32_e32 v72, v28
	v_mov_b32_e32 v73, v32
	v_pk_fma_f32 v[70:71], v[72:73], v[72:73], v[70:71]
	v_mov_b32_e32 v72, v29
	v_mov_b32_e32 v73, v33
	v_pk_fma_f32 v[70:71], v[72:73], v[72:73], v[70:71]
	v_mov_b32_e32 v72, v18
	v_mov_b32_e32 v73, v22
	v_pk_mul_f32 v[72:73], v[72:73], v[72:73]
	v_mov_b32_e32 v80, v19
	v_mov_b32_e32 v81, v23
	v_pk_fma_f32 v[72:73], v[80:81], v[80:81], v[72:73]
	v_mov_b32_e32 v80, v20
	v_mov_b32_e32 v81, v24
	v_pk_fma_f32 v[72:73], v[80:81], v[80:81], v[72:73]
	v_mov_b32_e32 v80, v21
	v_mov_b32_e32 v81, v25
	v_pk_fma_f32 v[72:73], v[80:81], v[80:81], v[72:73]
	v_add_f32_e32 v70, v70, v71
	v_add_f32_e32 v70, v73, v70
	v_add_f32_e32 v70, v72, v70
	v_mov_b32_e32 v71, v70
	s_nop 1
	v_permlane32_swap_b32_e32 v70, v71
	v_add_f32_e32 v70, v70, v71
	v_mov_b32_e32 v71, v70
	s_nop 1
	v_permlane16_swap_b32_e32 v70, v71
	v_add_f32_e32 v70, v70, v71
	s_nop 1
	v_add_f32_dpp v70, v70, v70 row_ror:8 row_mask:0xf bank_mask:0xf
	s_nop 1
	v_add_f32_dpp v70, v70, v70 row_ror:4 row_mask:0xf bank_mask:0xf
	s_nop 1
	v_add_f32_dpp v70, v70, v70 quad_perm:[2,3,0,1] row_mask:0xf bank_mask:0xf
	s_nop 1
	v_add_f32_dpp v70, v70, v70 quad_perm:[1,0,3,2] row_mask:0xf bank_mask:0xf
	s_nop 0
	v_fmamk_f32 v70, v70, 0x3a800000, v170
	v_cmp_gt_f32_e32 vcc, s16, v70
	v_mul_f32_e32 v71, 0x4b800000, v70
	s_mov_b32 s16, 0xf8200000
	v_cndmask_b32_e32 v70, v70, v71, vcc
	v_rsq_f32_e32 v70, v70
	s_nop 0
	v_mul_f32_e32 v71, 0x45800000, v70
	v_cndmask_b32_e32 v70, v70, v71, vcc
	v_pk_mul_f32 v[30:31], v[30:31], v[70:71] op_sel_hi:[1,0]
	v_pk_mul_f32 v[32:33], v[32:33], v[70:71] op_sel_hi:[1,0]
	v_pk_fma_f32 v[30:31], v[52:53], v[30:31], v[2:3]
	v_pk_fma_f32 v[32:33], v[50:51], v[32:33], v[4:5]
	v_cvt_pk_bf16_f32 v30, v30, v31
	v_cvt_pk_bf16_f32 v31, v32, v33
	v_add_co_u32_e32 v32, vcc, s16, v68
	v_pk_mul_f32 v[26:27], v[26:27], v[70:71] op_sel_hi:[1,0]
	v_pk_mul_f32 v[28:29], v[28:29], v[70:71] op_sel_hi:[1,0]
	v_addc_co_u32_e32 v33, vcc, -1, v69, vcc
	v_pk_fma_f32 v[26:27], v[56:57], v[26:27], v[6:7]
	v_pk_fma_f32 v[28:29], v[54:55], v[28:29], v[8:9]
	s_mov_b32 s16, 0xf8201000
	v_pk_mul_f32 v[22:23], v[22:23], v[70:71] op_sel_hi:[1,0]
	v_pk_mul_f32 v[24:25], v[24:25], v[70:71] op_sel_hi:[1,0]
	v_pk_mul_f32 v[18:19], v[18:19], v[70:71] op_sel_hi:[1,0]
	v_pk_mul_f32 v[20:21], v[20:21], v[70:71] op_sel_hi:[1,0]
	v_cvt_pk_bf16_f32 v26, v26, v27
	v_cvt_pk_bf16_f32 v27, v28, v29
	v_add_co_u32_e32 v28, vcc, s16, v68
	v_pk_fma_f32 v[22:23], v[60:61], v[22:23], v[10:11]
	v_pk_fma_f32 v[24:25], v[58:59], v[24:25], v[12:13]
	v_pk_fma_f32 v[18:19], v[62:63], v[18:19], v[14:15]
	v_pk_fma_f32 v[20:21], v[64:65], v[20:21], v[16:17]
	v_addc_co_u32_e32 v29, vcc, -1, v69, vcc
	v_cvt_pk_bf16_f32 v22, v22, v23
	v_cvt_pk_bf16_f32 v23, v24, v25
	v_cvt_pk_bf16_f32 v18, v18, v19
	v_cvt_pk_bf16_f32 v19, v20, v21
	global_store_dwordx2 v[32:33], v[30:31], off
	global_store_dwordx2 v[28:29], v[26:27], off offset:-3584
	global_store_dwordx2 v[28:29], v[22:23], off offset:-3072
	global_store_dwordx2 v[28:29], v[18:19], off offset:-2560
	s_branch .LBB0_654
